# grid-barrier seams before GEMM phases: waves 1-7 touch the next phase's weight copy (prefetch into memory-side cache)
# speedup vs baseline: 1.0032x; 1.0032x over previous
.LBB0_513:
	v_readlane_b32 s88, v250, 45
	s_cmp_lt_i32 s85, 6
	v_readlane_b32 s89, v250, 46
	s_cbranch_scc1 .LBB0_567
	s_waitcnt vmcnt(0)
	s_waitcnt vmcnt(0) lgkmcnt(0)
	s_barrier
	v_readlane_b32 s98, v250, 21
	s_nop 3
	s_cmp_eq_u32 s98, 0
	s_cbranch_scc1 .Lpf_skip_5
	s_mul_i32 s99, s33, 7
	s_add_i32 s99, s99, s98
	s_add_i32 s99, s99, -1
	s_mul_i32 s99, s99, 0x2000
	v_lshlrev_b32_e32 v251, 7, v178
	v_add_u32_e32 v251, s99, v251
	s_add_u32 s100, s88, 0x1900000
	s_addc_u32 s101, s89, 0
	global_load_dword v252, v251, s[100:101]
.Lpf_skip_5:
	s_mov_b64 s[0:1], exec
	v_readlane_b32 s2, v250, 19
	v_readlane_b32 s3, v250, 20
	s_and_b64 s[2:3], s[0:1], s[2:3]
	s_mov_b64 exec, s[2:3]
	s_cbranch_execz .LBB0_566
	s_add_i32 s2, 0, 0x21020
	v_mov_b32_e32 v1, s2
	s_waitcnt vmcnt(0) expcnt(0) lgkmcnt(0)
	ds_read_b32 v3, v1
	s_add_i32 s2, 0, 0x21024
	v_mov_b32_e32 v1, s2
	ds_read_b32 v1, v1
	s_waitcnt lgkmcnt(1)
	v_cmp_ne_u32_e32 vcc, 0, v3
	s_cbranch_vccnz .LBB0_530
	v_readlane_b32 s2, v250, 0
	v_readlane_b32 s3, v250, 1
	s_load_dwordx2 s[6:7], s[2:3], 0x4
	s_add_u32 s2, s86, 0x1000
	s_addc_u32 s3, s87, 0
	s_add_u32 s4, s86, 0x1100
	s_addc_u32 s5, s87, 0
	s_waitcnt lgkmcnt(0)
	s_mul_i32 s16, s6, s61
	s_add_u32 s6, s86, 0x1200
	s_mul_i32 s16, s16, s7
	s_addc_u32 s7, s87, 0
	s_add_u32 s8, s86, 0x1300
	s_addc_u32 s9, s87, 0
	s_mov_b32 s17, 1
	v_mov_b32_e32 v17, 0
	s_branch .LBB0_518

.LBB0_672:
	s_cmp_lt_i32 s85, 8
	s_barrier
	s_cbranch_scc1 .LBB0_726
	s_waitcnt vmcnt(0)
	s_barrier
	v_readlane_b32 s98, v250, 21
	s_nop 3
	s_cmp_eq_u32 s98, 0
	s_cbranch_scc1 .Lpf_skip_7
	s_mul_i32 s99, s33, 7
	s_add_i32 s99, s99, s98
	s_add_i32 s99, s99, -1
	s_mul_i32 s99, s99, 0x8000
	v_lshlrev_b32_e32 v251, 7, v178
	v_add_u32_e32 v251, s99, v251
	s_add_u32 s100, s88, 0x7500000
	s_addc_u32 s101, s89, 0
	global_load_dword v252, v251, s[100:101]
	v_add_u32_e32 v251, 0x2000, v251
	global_load_dword v253, v251, s[100:101]
	v_add_u32_e32 v251, 0x2000, v251
	global_load_dword v254, v251, s[100:101]
	v_add_u32_e32 v251, 0x2000, v251
	global_load_dword v255, v251, s[100:101]

.LBB0_769:
	s_cmp_lt_i32 s85, 9
	s_cbranch_scc1 .LBB0_823
	s_waitcnt vmcnt(0)
	s_waitcnt vmcnt(0) lgkmcnt(0)
	s_barrier
	v_readlane_b32 s98, v250, 21
	s_nop 3
	s_cmp_eq_u32 s98, 0
	s_cbranch_scc1 .Lpf_skip_8
	s_mul_i32 s99, s33, 7
	s_add_i32 s99, s99, s98
	s_add_i32 s99, s99, -1
	s_mul_i32 s99, s99, 0x4000
	v_lshlrev_b32_e32 v251, 7, v178
	v_add_u32_e32 v251, s99, v251
	s_add_u32 s100, s88, 0x12500000
	s_addc_u32 s101, s89, 0
	global_load_dword v252, v251, s[100:101]
	v_add_u32_e32 v251, 0x2000, v251
	global_load_dword v253, v251, s[100:101]

.LBB0_971:
	s_cmp_lt_i32 s85, 11
	s_barrier
	s_cbranch_scc1 .LBB0_1025
	s_waitcnt vmcnt(0)
	s_barrier
	v_readlane_b32 s98, v250, 21
	s_nop 3
	s_cmp_eq_u32 s98, 0
	s_cbranch_scc1 .Lpf_skip_10
	s_mul_i32 s99, s33, 7
	s_add_i32 s99, s99, s98
	s_add_i32 s99, s99, -1
	s_mul_i32 s99, s99, 0x4000
	v_lshlrev_b32_e32 v251, 7, v178
	v_add_u32_e32 v251, s99, v251
	s_add_u32 s100, s88, 0x2100000
	s_addc_u32 s101, s89, 0
	global_load_dword v252, v251, s[100:101]
	v_add_u32_e32 v251, 0x2000, v251
	global_load_dword v253, v251, s[100:101]

.LBB0_1573:
	s_cmp_lt_i32 s85, 16
	s_barrier
	s_cbranch_scc1 .LBB0_1627
	s_waitcnt vmcnt(0)
	s_barrier
	v_readlane_b32 s98, v250, 21
	s_nop 3
	s_cmp_eq_u32 s98, 0
	s_cbranch_scc1 .Lpf_skip_15
	s_mul_i32 s99, s33, 7
	s_add_i32 s99, s99, s98
	s_add_i32 s99, s99, -1
	s_mul_i32 s99, s99, 0x8000
	v_lshlrev_b32_e32 v251, 7, v178
	v_add_u32_e32 v251, s99, v251
	s_add_u32 s100, s88, 0xa100000
	s_addc_u32 s101, s89, 0
	global_load_dword v252, v251, s[100:101]
	v_add_u32_e32 v251, 0x2000, v251
	global_load_dword v253, v251, s[100:101]
	v_add_u32_e32 v251, 0x2000, v251
	global_load_dword v254, v251, s[100:101]
	v_add_u32_e32 v251, 0x2000, v251
	global_load_dword v255, v251, s[100:101]

.LBB0_1650:
	s_cmp_lt_i32 s85, 17
	s_cbranch_scc1 .LBB0_1704
	s_waitcnt vmcnt(0)
	s_waitcnt vmcnt(0) lgkmcnt(0)
	s_barrier
	v_readlane_b32 s98, v250, 21
	s_nop 3
	s_cmp_eq_u32 s98, 0
	s_cbranch_scc1 .Lpf_skip_16
	s_mul_i32 s99, s33, 7
	s_add_i32 s99, s99, s98
	s_add_i32 s99, s99, -1
	s_mul_i32 s99, s99, 0x4000
	v_lshlrev_b32_e32 v251, 7, v178
	v_add_u32_e32 v251, s99, v251
	s_add_u32 s100, s88, 0x13b00000
	s_addc_u32 s101, s89, 0
	global_load_dword v252, v251, s[100:101]
	v_add_u32_e32 v251, 0x2000, v251
	global_load_dword v253, v251, s[100:101]

.LBB0_1839:
	s_cmp_lt_i32 s85, 19
	s_barrier
	s_cbranch_scc1 .LBB0_1893
	s_waitcnt vmcnt(0)
	s_barrier
	v_readlane_b32 s98, v250, 21
	s_nop 3
	s_cmp_eq_u32 s98, 0
	s_cbranch_scc1 .Lpf_skip_18
	s_mul_i32 s99, s33, 7
	s_add_i32 s99, s99, s98
	s_add_i32 s99, s99, -1
	s_mul_i32 s99, s99, 0x2000
	v_lshlrev_b32_e32 v251, 7, v178
	v_add_u32_e32 v251, s99, v251
	s_add_u32 s100, s88, 0x4100000
	s_addc_u32 s101, s89, 0
	global_load_dword v252, v251, s[100:101]

.LBB0_2032:
	s_cmp_lt_i32 s85, 20
	s_cbranch_scc1 .LBB0_2086
	s_waitcnt vmcnt(0)
	s_waitcnt vmcnt(0) lgkmcnt(0)
	s_barrier
	v_readlane_b32 s98, v250, 21
	s_nop 3
	s_cmp_eq_u32 s98, 0
	s_cbranch_scc1 .Lpf_skip_19
	s_mul_i32 s99, s33, 7
	s_add_i32 s99, s99, s98
	s_add_i32 s99, s99, -1
	s_mul_i32 s99, s99, 0x2000
	v_lshlrev_b32_e32 v251, 7, v178
	v_add_u32_e32 v251, s99, v251
	s_add_u32 s100, s88, 0x4600000
	s_addc_u32 s101, s89, 0
	global_load_dword v252, v251, s[100:101]
.Lpf_skip_19:
	s_mov_b64 s[0:1], exec
	v_readlane_b32 s2, v250, 19
	v_readlane_b32 s3, v250, 20
	s_and_b64 s[2:3], s[0:1], s[2:3]
	s_mov_b64 exec, s[2:3]
	s_cbranch_execz .LBB0_2085
	s_add_i32 s2, 0, 0x21020
	v_mov_b32_e32 v1, s2
	s_waitcnt vmcnt(0) expcnt(0) lgkmcnt(0)
	ds_read_b32 v3, v1
	s_add_i32 s2, 0, 0x21024
	v_mov_b32_e32 v1, s2
	ds_read_b32 v1, v1
	s_waitcnt lgkmcnt(1)
	v_cmp_ne_u32_e32 vcc, 0, v3
	s_cbranch_vccnz .LBB0_2049
	v_readlane_b32 s2, v250, 0
	v_readlane_b32 s3, v250, 1
	s_load_dwordx2 s[6:7], s[2:3], 0x4
	s_add_u32 s2, s86, 0x1000
	s_addc_u32 s3, s87, 0
	s_add_u32 s4, s86, 0x1100
	s_addc_u32 s5, s87, 0
	s_waitcnt lgkmcnt(0)
	s_mul_i32 s18, s6, s61
	s_add_u32 s6, s86, 0x1200
	s_mul_i32 s18, s18, s7
	s_addc_u32 s7, s87, 0
	s_add_u32 s8, s86, 0x1300
	s_addc_u32 s9, s87, 0
	s_mov_b32 s19, 1
	v_mov_b32_e32 v17, 0
	s_branch .LBB0_2037

.LBB0_2244:
	s_cmp_lt_i32 s85, 22
	s_cbranch_scc1 .LBB0_2298
	s_waitcnt vmcnt(0)
	s_waitcnt vmcnt(0)
	s_barrier
	v_readlane_b32 s98, v250, 21
	s_nop 3
	s_cmp_eq_u32 s98, 0
	s_cbranch_scc1 .Lpf_skip_21
	s_mul_i32 s99, s33, 7
	s_add_i32 s99, s99, s98
	s_add_i32 s99, s99, -1
	s_mul_i32 s99, s99, 0x2000
	v_lshlrev_b32_e32 v251, 7, v178
	v_add_u32_e32 v251, s99, v251
	s_add_u32 s100, s88, 0x4d00000
	s_addc_u32 s101, s89, 0
	global_load_dword v252, v251, s[100:101]

.LBB0_2403:
	s_cmp_lt_i32 s85, 24
	s_barrier
	s_cbranch_scc1 .LBB0_2457
	s_waitcnt vmcnt(0)
	s_barrier
	v_readlane_b32 s98, v250, 21
	s_nop 3
	s_cmp_eq_u32 s98, 0
	s_cbranch_scc1 .Lpf_skip_23
	s_mul_i32 s99, s33, 7
	s_add_i32 s99, s99, s98
	s_add_i32 s99, s99, -1
	s_mul_i32 s99, s99, 0x8000
	v_lshlrev_b32_e32 v251, 7, v178
	v_add_u32_e32 v251, s99, v251
	s_add_u32 s100, s88, 0xcd00000
	s_addc_u32 s101, s89, 0
	global_load_dword v252, v251, s[100:101]
	v_add_u32_e32 v251, 0x2000, v251
	global_load_dword v253, v251, s[100:101]
	v_add_u32_e32 v251, 0x2000, v251
	global_load_dword v254, v251, s[100:101]
	v_add_u32_e32 v251, 0x2000, v251
	global_load_dword v255, v251, s[100:101]

.LBB0_2480:
	s_cmp_lt_i32 s85, 25
	s_cbranch_scc1 .LBB0_2534
	s_waitcnt vmcnt(0)
	s_waitcnt vmcnt(0) lgkmcnt(0)
	s_barrier
	v_readlane_b32 s98, v250, 21
	s_nop 3
	s_cmp_eq_u32 s98, 0
	s_cbranch_scc1 .Lpf_skip_24
	s_mul_i32 s99, s33, 7
	s_add_i32 s99, s99, s98
	s_add_i32 s99, s99, -1
	s_mul_i32 s99, s99, 0x4000
	v_lshlrev_b32_e32 v251, 7, v178
	v_add_u32_e32 v251, s99, v251
	s_add_u32 s100, s88, 0x15100000
	s_addc_u32 s101, s89, 0
	global_load_dword v252, v251, s[100:101]
	v_add_u32_e32 v251, 0x2000, v251
	global_load_dword v253, v251, s[100:101]

.LBB0_2665:
	s_cmp_lt_i32 s85, 27
	s_barrier
	s_cbranch_scc1 .LBB0_2719
	s_waitcnt vmcnt(0)
	s_barrier
	v_readlane_b32 s98, v250, 21
	s_nop 3
	s_cmp_eq_u32 s98, 0
	s_cbranch_scc1 .Lpf_skip_26
	s_mul_i32 s99, s33, 7
	s_add_i32 s99, s99, s98
	s_add_i32 s99, s99, -1
	s_mul_i32 s99, s99, 0x4000
	v_lshlrev_b32_e32 v251, 7, v178
	v_add_u32_e32 v251, s99, v251
	s_add_u32 s100, s88, 0x5500000
	s_addc_u32 s101, s89, 0
	global_load_dword v252, v251, s[100:101]
	v_add_u32_e32 v251, 0x2000, v251
	global_load_dword v253, v251, s[100:101]

.LBB0_2988:
	s_cmp_lt_i32 s85, 29
	s_cbranch_scc1 .LBB0_3042
	s_waitcnt vmcnt(0)
	s_waitcnt vmcnt(0) lgkmcnt(0)
	s_barrier
	v_readlane_b32 s98, v250, 21
	s_nop 3
	s_cmp_eq_u32 s98, 0
	s_cbranch_scc1 .Lpf_skip_28
	s_mul_i32 s99, s33, 7
	s_add_i32 s99, s99, s98
	s_add_i32 s99, s99, -1
	s_mul_i32 s99, s99, 0x2000
	v_lshlrev_b32_e32 v251, 7, v178
	v_add_u32_e32 v251, s99, v251
	s_add_u32 s100, s88, 0x6d00000
	s_addc_u32 s101, s89, 0
	global_load_dword v252, v251, s[100:101]

.LBB0_3127:
	s_cmp_lt_i32 s85, 31
	s_barrier
	s_cbranch_scc1 .LBB0_3181
	s_waitcnt vmcnt(0)
	s_barrier
	v_readlane_b32 s98, v250, 21
	s_nop 3
	s_cmp_eq_u32 s98, 0
	s_cbranch_scc1 .Lpf_skip_30
	s_mul_i32 s99, s33, 7
	s_add_i32 s99, s99, s98
	s_add_i32 s99, s99, -1
	s_mul_i32 s99, s99, 0x8000
	v_lshlrev_b32_e32 v251, 7, v178
	v_add_u32_e32 v251, s99, v251
	s_add_u32 s100, s88, 0xf900000
	s_addc_u32 s101, s89, 0
	global_load_dword v252, v251, s[100:101]
	v_add_u32_e32 v251, 0x2000, v251
	global_load_dword v253, v251, s[100:101]
	v_add_u32_e32 v251, 0x2000, v251
	global_load_dword v254, v251, s[100:101]
	v_add_u32_e32 v251, 0x2000, v251
	global_load_dword v255, v251, s[100:101]

.LBB0_3198:
	s_cmp_lt_i32 s85, 32
	s_cbranch_scc1 .LBB0_3252
	s_waitcnt vmcnt(0)
	s_waitcnt vmcnt(0) lgkmcnt(0)
	s_barrier
	v_readlane_b32 s98, v250, 21
	s_nop 3
	s_cmp_eq_u32 s98, 0
	s_cbranch_scc1 .Lpf_skip_31
	s_mul_i32 s99, s33, 7
	s_add_i32 s99, s99, s98
	s_add_i32 s99, s99, -1
	s_mul_i32 s99, s99, 0x4000
	v_lshlrev_b32_e32 v251, 7, v178
	v_add_u32_e32 v251, s99, v251
	s_add_u32 s100, s88, 0x16700000
	s_addc_u32 s101, s89, 0
	global_load_dword v252, v251, s[100:101]
	v_add_u32_e32 v251, 0x2000, v251
	global_load_dword v253, v251, s[100:101]

	.amdhsa_kernel _Z10fwd_kernel4Args
		.amdhsa_group_segment_fixed_size 0
		.amdhsa_private_segment_fixed_size 0
		.amdhsa_kernarg_size 488
		.amdhsa_user_sgpr_count 2
		.amdhsa_user_sgpr_dispatch_ptr 0
		.amdhsa_user_sgpr_queue_ptr 0
		.amdhsa_user_sgpr_kernarg_segment_ptr 1
		.amdhsa_user_sgpr_dispatch_id 0
		.amdhsa_user_sgpr_kernarg_preload_length 0
		.amdhsa_user_sgpr_kernarg_preload_offset 0
		.amdhsa_user_sgpr_private_segment_size 0
		.amdhsa_uses_dynamic_stack 0
		.amdhsa_enable_private_segment 0
		.amdhsa_system_sgpr_workgroup_id_x 1
		.amdhsa_system_sgpr_workgroup_id_y 0
		.amdhsa_system_sgpr_workgroup_id_z 0
		.amdhsa_system_sgpr_workgroup_info 0
		.amdhsa_system_vgpr_workitem_id 0
		.amdhsa_next_free_vgpr 256
		.amdhsa_next_free_sgpr 102
		.amdhsa_accum_offset 256
		.amdhsa_reserve_vcc 1
		.amdhsa_float_round_mode_32 0
		.amdhsa_float_round_mode_16_64 0
		.amdhsa_float_denorm_mode_32 3
		.amdhsa_float_denorm_mode_16_64 3
		.amdhsa_dx10_clamp 1
		.amdhsa_ieee_mode 1
		.amdhsa_fp16_overflow 0
		.amdhsa_tg_split 0
		.amdhsa_exception_fp_ieee_invalid_op 0
		.amdhsa_exception_fp_denorm_src 0
		.amdhsa_exception_fp_ieee_div_zero 0
		.amdhsa_exception_fp_ieee_overflow 0
		.amdhsa_exception_fp_ieee_underflow 0
		.amdhsa_exception_fp_ieee_inexact 0
		.amdhsa_exception_int_div_zero 0
	.end_amdhsa_kernel

amdhsa.kernels:
  - .agpr_count:     0
    .args:
      - .offset:         0
        .size:           232
        .value_kind:     by_value
      - .offset:         232
        .size:           4
        .value_kind:     hidden_block_count_x
      - .offset:         236
        .size:           4
        .value_kind:     hidden_block_count_y
      - .offset:         240
        .size:           4
        .value_kind:     hidden_block_count_z
      - .offset:         244
        .size:           2
        .value_kind:     hidden_group_size_x
      - .offset:         246
        .size:           2
        .value_kind:     hidden_group_size_y
      - .offset:         248
        .size:           2
        .value_kind:     hidden_group_size_z
      - .offset:         250
        .size:           2
        .value_kind:     hidden_remainder_x
      - .offset:         252
        .size:           2
        .value_kind:     hidden_remainder_y
      - .offset:         254
        .size:           2
        .value_kind:     hidden_remainder_z
      - .offset:         272
        .size:           8
        .value_kind:     hidden_global_offset_x
      - .offset:         280
        .size:           8
        .value_kind:     hidden_global_offset_y
      - .offset:         288
        .size:           8
        .value_kind:     hidden_global_offset_z
      - .offset:         296
        .size:           2
        .value_kind:     hidden_grid_dims
      - .offset:         352
        .size:           4
        .value_kind:     hidden_dynamic_lds_size
    .group_segment_fixed_size: 0
    .kernarg_segment_align: 8
    .kernarg_segment_size: 488
    .language:       OpenCL C
    .language_version:
      - 2
      - 0
    .max_flat_workgroup_size: 512
    .name:           _Z10fwd_kernel4Args
    .private_segment_fixed_size: 0
    .sgpr_count:     108
    .sgpr_spill_count: 47
    .symbol:         _Z10fwd_kernel4Args.kd
    .uniform_work_group_size: 1
    .uses_dynamic_stack: false
    .vgpr_count:     256
    .vgpr_spill_count: 0
    .wavefront_size: 64
